# attention QK block: the 11-state wait for the MFMA result before the row max now carries the PV block's LDS address arithmetic (4 VALU moved into the MFMA shadow, s_nop 10 -> s_nop 6), on top of the m
# speedup vs baseline: 1.0071x; 1.0027x over previous
.LBB0_1046:
	s_or_b64 exec, exec, s[22:23]
	global_load_dwordx4 v[152:155], v[168:169], off
	s_and_b32 s25, s4, 1
	v_cmp_le_i32_e32 vcc, s4, v185
	s_and_saveexec_b64 s[22:23], vcc
	s_cbranch_execz .LBB0_1052
	s_mul_i32 s26, s25, 0x5600
	s_add_i32 s26, s26, 0
	v_add3_u32 v187, s26, v184, v166
	ds_read_b128 v[64:67], v187
	ds_read_b128 v[188:191], v187 offset:32
	s_waitcnt lgkmcnt(1)
	v_mfma_f32_32x32x16_bf16 v[80:95], v[64:67], v[132:135], 0
	v_mfma_f32_32x32x16_bf16 v[64:79], v[64:67], v[140:143], 0
	s_waitcnt lgkmcnt(0)
	v_mfma_f32_32x32x16_bf16 v[80:95], v[188:191], v[124:127], v[80:95]
	v_mfma_f32_32x32x16_bf16 v[64:79], v[188:191], v[136:139], v[64:79]
	ds_read_b128 v[188:191], v187 offset:64
	ds_read_b128 v[192:195], v187 offset:96
	s_waitcnt lgkmcnt(1)
	v_mfma_f32_32x32x16_bf16 v[80:95], v[188:191], v[120:123], v[80:95]
	s_waitcnt lgkmcnt(0)
	v_mfma_f32_32x32x16_bf16 v[80:95], v[192:195], v[116:119], v[80:95]
	v_mfma_f32_32x32x16_bf16 v[64:79], v[188:191], v[128:131], v[64:79]
	ds_read_b128 v[188:191], v187 offset:128
	ds_read_b128 v[196:199], v187 offset:160
	s_nop 1
	s_waitcnt lgkmcnt(1)
	v_mfma_f32_32x32x16_bf16 v[80:95], v[188:191], v[112:115], v[80:95]
	s_waitcnt lgkmcnt(0)
	v_mfma_f32_32x32x16_bf16 v[80:95], v[196:199], v[108:111], v[80:95]
	v_mfma_f32_32x32x16_bf16 v[64:79], v[192:195], v[104:107], v[64:79]
	v_lshl_add_u32 v201, v179, 1, s26
	v_add3_u32 v202, v201, v158, v178
	v_add_u32_e32 v201, 0x3000, v202
	v_add_u32_e32 v202, 0x4000, v202
	s_nop 6
	v_max_f32_e32 v200, v81, v81
	v_max_f32_e32 v192, v80, v80
	v_max_f32_e32 v192, v192, v200
	v_max3_f32 v192, v192, v82, v83
	v_max3_f32 v192, v192, v84, v85
	v_max3_f32 v192, v192, v86, v87
	v_max3_f32 v192, v192, v88, v89
	v_mfma_f32_32x32x16_bf16 v[64:79], v[188:191], v[100:103], v[64:79]
	v_max3_f32 v192, v192, v90, v91
	v_max3_f32 v188, v192, v92, v93
	v_max3_f32 v188, v188, v94, v95
	v_mov_b32_e32 v189, v188
	s_nop 1
	v_permlane32_swap_b32_e32 v189, v188
	s_waitcnt lgkmcnt(0)
	v_max_f32_e32 v189, v189, v189
	v_mfma_f32_32x32x16_bf16 v[64:79], v[196:199], v[96:99], v[64:79]
	v_max_f32_e32 v188, v188, v189
	v_add_f32_e32 v189, 0x41000000, v161
	v_cmp_gt_f32_e32 vcc, v188, v189
	s_cbranch_vccz .LBB0_1049
	v_max_f32_e32 v188, v188, v188
	v_max_f32_e32 v189, v161, v161
	v_max_f32_e32 v189, v189, v188
	v_sub_f32_e32 v161, v161, v189
	v_exp_f32_e32 v188, v161
	v_mov_b32_e32 v161, v189
	v_mul_f32_e32 v162, v162, v188
	v_pk_mul_f32 v[62:63], v[62:63], v[188:189] op_sel_hi:[1,0]
	v_pk_mul_f32 v[60:61], v[60:61], v[188:189] op_sel_hi:[1,0]
	v_pk_mul_f32 v[58:59], v[58:59], v[188:189] op_sel_hi:[1,0]
	v_pk_mul_f32 v[56:57], v[56:57], v[188:189] op_sel_hi:[1,0]
	v_pk_mul_f32 v[54:55], v[54:55], v[188:189] op_sel_hi:[1,0]
	v_pk_mul_f32 v[52:53], v[52:53], v[188:189] op_sel_hi:[1,0]
	v_pk_mul_f32 v[50:51], v[50:51], v[188:189] op_sel_hi:[1,0]
	v_pk_mul_f32 v[48:49], v[48:49], v[188:189] op_sel_hi:[1,0]
	v_pk_mul_f32 v[46:47], v[46:47], v[188:189] op_sel_hi:[1,0]
	v_pk_mul_f32 v[44:45], v[44:45], v[188:189] op_sel_hi:[1,0]
	v_pk_mul_f32 v[42:43], v[42:43], v[188:189] op_sel_hi:[1,0]
	v_pk_mul_f32 v[40:41], v[40:41], v[188:189] op_sel_hi:[1,0]
	v_pk_mul_f32 v[38:39], v[38:39], v[188:189] op_sel_hi:[1,0]
	v_pk_mul_f32 v[36:37], v[36:37], v[188:189] op_sel_hi:[1,0]
	v_pk_mul_f32 v[34:35], v[34:35], v[188:189] op_sel_hi:[1,0]
	v_pk_mul_f32 v[32:33], v[32:33], v[188:189] op_sel_hi:[1,0]

.LBB0_1051:
	v_pk_add_f32 v[208:209], v[64:65], v[166:167] op_sel:[0,1] op_sel_hi:[1,1] neg_lo:[0,1] neg_hi:[0,1]
	v_pk_add_f32 v[210:211], v[66:67], v[166:167] op_sel:[0,1] op_sel_hi:[1,1] neg_lo:[0,1] neg_hi:[0,1]
	v_pk_add_f32 v[212:213], v[68:69], v[166:167] op_sel:[0,1] op_sel_hi:[1,1] neg_lo:[0,1] neg_hi:[0,1]
	v_pk_add_f32 v[214:215], v[70:71], v[166:167] op_sel:[0,1] op_sel_hi:[1,1] neg_lo:[0,1] neg_hi:[0,1]
	v_pk_add_f32 v[216:217], v[72:73], v[166:167] op_sel:[0,1] op_sel_hi:[1,1] neg_lo:[0,1] neg_hi:[0,1]
	v_pk_add_f32 v[218:219], v[74:75], v[166:167] op_sel:[0,1] op_sel_hi:[1,1] neg_lo:[0,1] neg_hi:[0,1]
	v_pk_add_f32 v[220:221], v[76:77], v[166:167] op_sel:[0,1] op_sel_hi:[1,1] neg_lo:[0,1] neg_hi:[0,1]
	v_pk_add_f32 v[222:223], v[78:79], v[166:167] op_sel:[0,1] op_sel_hi:[1,1] neg_lo:[0,1] neg_hi:[0,1]
	v_exp_f32_e32 v190, v208
	ds_read2_b64 v[64:67], v201 offset0:128 offset1:130
	v_exp_f32_e32 v191, v209
	v_exp_f32_e32 v192, v210
	v_exp_f32_e32 v193, v211
	v_exp_f32_e32 v194, v212
	v_cvt_pk_bf16_f32 v70, v92, v93
	v_exp_f32_e32 v195, v213
	v_exp_f32_e32 v92, v214
	v_exp_f32_e32 v93, v215
	v_cvt_pk_bf16_f32 v68, v88, v89
	v_cvt_pk_bf16_f32 v69, v90, v91
	v_cvt_pk_bf16_f32 v71, v94, v95
	v_cvt_pk_bf16_f32 v88, v190, v191
	v_cvt_pk_bf16_f32 v89, v192, v193
	v_cvt_pk_bf16_f32 v90, v194, v195
	v_cvt_pk_bf16_f32 v91, v92, v93
	s_waitcnt lgkmcnt(0)
	v_mfma_f32_32x32x16_bf16 v[48:63], v[64:67], v[68:71], v[48:63]
	v_exp_f32_e32 v196, v218
	v_mfma_f32_32x32x16_bf16 v[16:31], v[64:67], v[88:91], v[16:31]
	ds_read2_b64 v[64:67], v202 offset0:160 offset1:162
	v_exp_f32_e32 v197, v219
	v_exp_f32_e32 v74, v220
	v_exp_f32_e32 v75, v221
	s_waitcnt lgkmcnt(0)
	v_mfma_f32_32x32x16_bf16 v[32:47], v[64:67], v[68:71], v[32:47]
	v_exp_f32_e32 v94, v216
	v_exp_f32_e32 v95, v217
	ds_read2_b64 v[68:71], v201 offset0:132 offset1:134
	v_cvt_pk_bf16_f32 v73, v196, v197
	v_cvt_pk_bf16_f32 v72, v94, v95
	v_mfma_f32_32x32x16_bf16 v[0:15], v[64:67], v[88:91], v[0:15]
	v_exp_f32_e32 v88, v222
	v_exp_f32_e32 v89, v223
	ds_read2_b64 v[76:79], v202 offset0:164 offset1:166
	v_cvt_pk_bf16_f32 v64, v80, v81
	v_cvt_pk_bf16_f32 v65, v82, v83
	v_cvt_pk_bf16_f32 v66, v84, v85
	v_cvt_pk_bf16_f32 v67, v86, v87
	v_pk_add_f32 v[80:81], v[194:195], v[74:75]
	v_cvt_pk_bf16_f32 v74, v74, v75
	v_cvt_pk_bf16_f32 v75, v88, v89
	s_waitcnt lgkmcnt(1)
	v_mfma_f32_32x32x16_bf16 v[48:63], v[68:71], v[64:67], v[48:63]
	v_add_f32_e64 v82, v192, v196
	v_add_f32_e64 v83, v193, v197
	v_mfma_f32_32x32x16_bf16 v[16:31], v[68:71], v[72:75], v[16:31]
	v_add_f32_e64 v68, v190, v94
	v_add_f32_e64 v69, v191, v95
	v_add_f32_e64 v70, v92, v88
	v_add_f32_e64 v71, v93, v89
	v_add_f32_e64 v68, v68, v80
	v_add_f32_e64 v69, v69, v81
	v_pk_add_f32 v[70:71], v[82:83], v[70:71]
	s_nop 0
	v_pk_add_f32 v[68:69], v[68:69], v[70:71]
	s_nop 0
	v_add_f32_e32 v68, v68, v69
	s_waitcnt lgkmcnt(0)
	v_mfma_f32_32x32x16_bf16 v[32:47], v[76:79], v[64:67], v[32:47]
	v_mov_b32_e32 v64, v68
	s_nop 1
	v_permlane32_swap_b32_e32 v64, v68
	v_add_f32_e32 v65, v188, v189
	v_add_f32_e32 v162, v162, v65
	s_waitcnt lgkmcnt(0)
	v_add_f32_e32 v64, v68, v64
	v_add_f32_e32 v160, v160, v64
	v_mfma_f32_32x32x16_bf16 v[0:15], v[76:79], v[72:75], v[0:15]
